# adds: mixer B per-head epilogue gate loads issued together (counted waits); nt hint on the first rmsnorm's x loads
# speedup vs baseline: 1.0101x; 1.0021x over previous
.LBB0_691:
	v_add_co_u32_e32 v2, vcc, 0xffffd000, v98
	s_nop 1
	v_addc_co_u32_e32 v3, vcc, -1, v99, vcc
	global_load_dwordx4 v[62:65], v[2:3], off offset:-3072 nt
	global_load_dwordx4 v[58:61], v[2:3], off offset:-2048 nt
	global_load_dwordx4 v[54:57], v[2:3], off offset:-1024 nt
	global_load_dwordx4 v[50:53], v[2:3], off nt
	v_add_co_u32_e32 v2, vcc, 0xffffe000, v98
	s_waitcnt vmcnt(2)
	v_mul_f32_e32 v108, v59, v59
	v_addc_co_u32_e32 v3, vcc, -1, v99, vcc
	global_load_dwordx4 v[46:49], v[2:3], off offset:-3072 nt
	global_load_dwordx4 v[42:45], v[2:3], off offset:-2048 nt
	global_load_dwordx4 v[38:41], v[2:3], off offset:-1024 nt
	global_load_dwordx4 v[34:37], v[2:3], off nt
	v_add_co_u32_e32 v106, vcc, 0xfffff000, v98
	v_mul_f32_e32 v109, v61, v61
	s_nop 0
	v_addc_co_u32_e32 v107, vcc, -1, v99, vcc
	global_load_dwordx4 v[30:33], v[106:107], off offset:-3072 nt
	global_load_dwordx4 v[26:29], v[106:107], off offset:-2048 nt
	global_load_dwordx4 v[22:25], v[106:107], off offset:-1024 nt
	global_load_dwordx4 v[18:21], v[98:99], off offset:-4096 nt
	global_load_dwordx4 v[14:17], v[98:99], off offset:-3072 nt
	global_load_dwordx4 v[10:13], v[98:99], off offset:-2048 nt
	global_load_dwordx4 v[6:9], v[98:99], off offset:-1024 nt
	global_load_dwordx4 v[2:5], v[98:99], off nt
	v_mul_f32_e32 v106, v63, v63
	v_mul_f32_e32 v107, v65, v65
	s_waitcnt vmcnt(13)
	v_mul_f32_e32 v110, v55, v55
	v_mul_f32_e32 v111, v57, v57
	v_fmac_f32_e32 v106, v62, v62
	v_fmac_f32_e32 v107, v64, v64
	v_fmac_f32_e32 v108, v58, v58
	v_fmac_f32_e32 v109, v60, v60
	s_waitcnt vmcnt(12)
	v_mul_f32_e32 v112, v51, v51
	v_mul_f32_e32 v113, v53, v53
	v_fmac_f32_e32 v110, v54, v54
	v_fmac_f32_e32 v111, v56, v56
	v_add_f32_e32 v106, v106, v107
	v_add_f32_e32 v107, v108, v109
	v_fmac_f32_e32 v112, v50, v50
	v_fmac_f32_e32 v113, v52, v52
	v_add_f32_e32 v108, v110, v111
	v_add_f32_e32 v106, v106, v107
	v_add_f32_e32 v109, v112, v113
	v_add_f32_e32 v106, v106, v108
	v_add_f32_e32 v106, v106, v109
	s_waitcnt vmcnt(11)
	v_mul_f32_e32 v114, v47, v47
	v_mul_f32_e32 v115, v49, v49
	s_waitcnt vmcnt(10)
	v_mul_f32_e32 v116, v43, v43
	v_mul_f32_e32 v117, v45, v45
	v_fmac_f32_e32 v114, v46, v46
	v_fmac_f32_e32 v115, v48, v48
	s_waitcnt vmcnt(9)
	v_mul_f32_e32 v118, v39, v39
	v_mul_f32_e32 v119, v41, v41
	v_fmac_f32_e32 v116, v42, v42
	v_fmac_f32_e32 v117, v44, v44
	v_add_f32_e32 v107, v114, v115
	s_waitcnt vmcnt(8)
	v_mul_f32_e32 v120, v35, v35
	v_mul_f32_e32 v121, v37, v37
	v_fmac_f32_e32 v118, v38, v38
	v_fmac_f32_e32 v119, v40, v40
	v_add_f32_e32 v114, v116, v117
	v_add_f32_e32 v106, v106, v107
	v_fmac_f32_e32 v120, v34, v34
	v_fmac_f32_e32 v121, v36, v36
	s_waitcnt vmcnt(7)
	v_mul_f32_e32 v110, v31, v31
	v_mul_f32_e32 v111, v33, v33
	v_add_f32_e32 v115, v118, v119
	v_add_f32_e32 v106, v106, v114
	s_waitcnt vmcnt(6)
	v_mul_f32_e32 v112, v27, v27
	v_mul_f32_e32 v113, v29, v29
	v_add_f32_e32 v116, v120, v121
	v_fmac_f32_e32 v110, v30, v30
	v_fmac_f32_e32 v111, v32, v32
	v_add_f32_e32 v106, v106, v115
	s_waitcnt vmcnt(5)
	v_mul_f32_e32 v122, v23, v23
	v_mul_f32_e32 v123, v25, v25
	v_fmac_f32_e32 v112, v26, v26
	v_fmac_f32_e32 v113, v28, v28
	v_add_f32_e32 v108, v110, v111
	v_add_f32_e32 v106, v106, v116
	v_fmac_f32_e32 v122, v22, v22
	v_fmac_f32_e32 v123, v24, v24
	v_add_f32_e32 v110, v112, v113
	v_add_f32_e32 v106, v106, v108
	v_add_f32_e32 v106, v106, v110
	v_add_f32_e32 v107, v122, v123
	v_add_f32_e32 v106, v106, v107
	s_waitcnt vmcnt(4)
	v_mul_f32_e32 v107, v19, v19
	v_mul_f32_e32 v108, v21, v21
	v_fmac_f32_e32 v107, v18, v18
	v_fmac_f32_e32 v108, v20, v20
	v_add_f32_e32 v107, v107, v108
	global_load_dwordx4 v[110:113], v[68:69], off
	v_add_f32_e32 v106, v106, v107
	s_waitcnt vmcnt(4)
	v_mul_f32_e32 v107, v15, v15
	v_mul_f32_e32 v108, v17, v17
	v_fmac_f32_e32 v107, v14, v14
	v_fmac_f32_e32 v108, v16, v16
	v_add_f32_e32 v107, v107, v108
	v_add_f32_e32 v106, v106, v107
	s_waitcnt vmcnt(3)
	v_mul_f32_e32 v107, v11, v11
	v_mul_f32_e32 v108, v13, v13
	v_fmac_f32_e32 v107, v10, v10
	v_fmac_f32_e32 v108, v12, v12
	v_add_f32_e32 v107, v107, v108
	v_add_f32_e32 v106, v106, v107
	s_waitcnt vmcnt(2)
	v_mul_f32_e32 v107, v7, v7
	v_mul_f32_e32 v108, v9, v9
	v_fmac_f32_e32 v107, v6, v6
	v_fmac_f32_e32 v108, v8, v8
	v_add_f32_e32 v107, v107, v108
	v_add_f32_e32 v106, v106, v107
	s_waitcnt vmcnt(1)
	v_mul_f32_e32 v107, v3, v3
	v_mul_f32_e32 v108, v5, v5
	v_fmac_f32_e32 v107, v2, v2
	v_fmac_f32_e32 v108, v4, v4
	v_add_f32_e32 v107, v107, v108
	v_add_f32_e32 v106, v106, v107
	ds_bpermute_b32 v107, v100, v106
	s_waitcnt lgkmcnt(0)
	v_add_f32_e32 v106, v106, v107
	ds_bpermute_b32 v107, v101, v106
	s_waitcnt lgkmcnt(0)
	v_add_f32_e32 v106, v106, v107
	ds_bpermute_b32 v107, v102, v106
	s_waitcnt lgkmcnt(0)
	v_add_f32_e32 v106, v106, v107
	ds_bpermute_b32 v107, v103, v106
	s_waitcnt lgkmcnt(0)
	v_add_f32_e32 v106, v106, v107
	ds_bpermute_b32 v107, v104, v106
	s_waitcnt lgkmcnt(0)
	v_add_f32_e32 v106, v106, v107
	ds_bpermute_b32 v107, v105, v106
	s_waitcnt lgkmcnt(0)
	v_add_f32_e32 v106, v106, v107
	v_fmamk_f32 v106, v106, 0x39800000, v1
	v_mul_f32_e32 v107, 0x4f800000, v106
	v_cmp_gt_f32_e32 vcc, s2, v106
	s_nop 1
	v_cndmask_b32_e32 v106, v106, v107, vcc
	v_sqrt_f32_e32 v107, v106
	s_nop 0
	v_add_u32_e32 v108, -1, v107
	v_fma_f32 v109, -v108, v107, v106
	v_cmp_ge_f32_e64 s[6:7], 0, v109
	v_add_u32_e32 v109, 1, v107
	s_nop 0
	v_cndmask_b32_e64 v108, v107, v108, s[6:7]
	v_fma_f32 v107, -v109, v107, v106
	v_cmp_lt_f32_e64 s[6:7], 0, v107
	s_nop 1
	v_cndmask_b32_e64 v107, v108, v109, s[6:7]
	v_mul_f32_e32 v108, 0x37800000, v107
	v_cndmask_b32_e32 v107, v107, v108, vcc
	v_cmp_class_f32_e32 vcc, v106, v66
	s_nop 1
	v_cndmask_b32_e32 v106, v107, v106, vcc
	v_div_scale_f32 v107, s[6:7], v106, v106, 1.0
	v_rcp_f32_e32 v108, v107
	s_nop 0
	v_fma_f32 v109, -v107, v108, 1.0
	v_fmac_f32_e32 v108, v109, v108
	v_div_scale_f32 v109, vcc, 1.0, v106, 1.0
	v_mul_f32_e32 v114, v109, v108
	v_fma_f32 v115, -v107, v114, v109
	v_fmac_f32_e32 v114, v115, v108
	v_fma_f32 v107, -v107, v114, v109
	v_div_fmas_f32 v107, v107, v108, v114
	v_div_fixup_f32 v109, v107, v106, 1.0
	v_mul_f32_e32 v62, v62, v109
	s_waitcnt vmcnt(0)
	v_mul_f32_e32 v108, v110, v62
	v_mul_f32_e32 v62, v63, v109
	v_mul_f32_e32 v107, v111, v62
	v_mul_f32_e32 v62, v64, v109
	v_mul_f32_e32 v106, v112, v62
	v_mul_f32_e32 v62, v65, v109
	v_mul_f32_e32 v64, v113, v62
	v_bfe_u32 v62, v108, 16, 1
	v_add3_u32 v62, v108, v62, s13
	v_bfe_u32 v63, v107, 16, 1
	v_lshrrev_b32_e32 v62, 16, v62
	v_add3_u32 v63, v107, v63, s13
	v_and_or_b32 v110, v63, s14, v62
	v_bfe_u32 v62, v106, 16, 1
	v_add3_u32 v62, v106, v62, s13
	v_bfe_u32 v63, v64, 16, 1
	v_lshl_add_u64 v[114:115], s[10:11], 0, v[96:97]
	v_lshrrev_b32_e32 v62, 16, v62
	v_add3_u32 v63, v64, v63, s13
	v_and_or_b32 v111, v63, s14, v62
	v_add_co_u32_e32 v62, vcc, s22, v114
	v_mul_f32_e32 v58, v58, v109
	s_nop 0
	v_addc_co_u32_e32 v63, vcc, 0, v115, vcc
	global_store_dwordx2 v[62:63], v[110:111], off offset:-4096
	global_load_dwordx4 v[110:113], v[68:69], off offset:1024
	v_mul_f32_e32 v59, v59, v109
	v_mul_f32_e32 v65, v60, v109
	v_mul_f32_e32 v116, v61, v109
	v_add_co_u32_e32 v114, vcc, s15, v114
	v_mul_f32_e32 v54, v54, v109
	s_nop 0
	v_addc_co_u32_e32 v115, vcc, 0, v115, vcc
	v_mul_f32_e32 v55, v55, v109
	v_mul_f32_e32 v50, v50, v109
	v_mul_f32_e32 v51, v51, v109
	v_mul_f32_e32 v46, v46, v109
	v_mul_f32_e32 v47, v47, v109
	v_mul_f32_e32 v42, v42, v109
	v_mul_f32_e32 v43, v43, v109
	v_mul_f32_e32 v38, v38, v109
	v_mul_f32_e32 v39, v39, v109
	v_mul_f32_e32 v34, v34, v109
	v_mul_f32_e32 v35, v35, v109
	v_mul_f32_e32 v30, v30, v109
	v_mul_f32_e32 v31, v31, v109
	v_mul_f32_e32 v26, v26, v109
	v_mul_f32_e32 v27, v27, v109
	v_mul_f32_e32 v22, v22, v109
	v_mul_f32_e32 v23, v23, v109
	v_mul_f32_e32 v18, v18, v109
	v_mul_f32_e32 v19, v19, v109
	v_mul_f32_e32 v14, v14, v109
	v_mul_f32_e32 v15, v15, v109
	v_mul_f32_e32 v10, v10, v109
	v_mul_f32_e32 v11, v11, v109
	v_mul_f32_e32 v6, v6, v109
	v_mul_f32_e32 v7, v7, v109
	v_mul_f32_e32 v2, v2, v109
	v_mul_f32_e32 v3, v3, v109
	v_mul_f32_e32 v4, v4, v109
	s_waitcnt vmcnt(0)
	v_mul_f32_e32 v61, v110, v58
	v_mul_f32_e32 v60, v111, v59
	v_mul_f32_e32 v59, v112, v65
	v_mul_f32_e32 v58, v113, v116
	v_bfe_u32 v65, v61, 16, 1
	v_bfe_u32 v111, v59, 16, 1
	v_bfe_u32 v110, v60, 16, 1
	v_bfe_u32 v112, v58, 16, 1
	v_add3_u32 v65, v61, v65, s13
	v_add3_u32 v111, v59, v111, s13
	v_add3_u32 v110, v60, v110, s13
	v_add3_u32 v112, v58, v112, s13
	v_lshrrev_b32_e32 v65, 16, v65
	v_lshrrev_b32_e32 v111, 16, v111
	v_and_or_b32 v110, v110, s14, v65
	v_and_or_b32 v111, v112, s14, v111
	global_store_dwordx2 v[114:115], v[110:111], off offset:512
	global_load_dwordx4 v[110:113], v[68:69], off offset:2048
	v_mul_f32_e32 v65, v56, v109
	v_mul_f32_e32 v116, v57, v109
	s_waitcnt vmcnt(0)
	v_mul_f32_e32 v57, v110, v54
	v_mul_f32_e32 v56, v111, v55
	v_mul_f32_e32 v55, v112, v65
	v_mul_f32_e32 v54, v113, v116
	v_bfe_u32 v65, v57, 16, 1
	v_bfe_u32 v111, v55, 16, 1
	v_bfe_u32 v110, v56, 16, 1
	v_bfe_u32 v112, v54, 16, 1
	v_add3_u32 v65, v57, v65, s13
	v_add3_u32 v111, v55, v111, s13
	v_add3_u32 v110, v56, v110, s13
	v_add3_u32 v112, v54, v112, s13
	v_lshrrev_b32_e32 v65, 16, v65
	v_lshrrev_b32_e32 v111, 16, v111
	v_and_or_b32 v110, v110, s14, v65
	v_and_or_b32 v111, v112, s14, v111
	global_store_dwordx2 v[114:115], v[110:111], off offset:1024
	global_load_dwordx4 v[110:113], v[68:69], off offset:3072
	v_mul_f32_e32 v65, v52, v109
	v_mul_f32_e32 v116, v53, v109
	s_waitcnt vmcnt(0)
	v_mul_f32_e32 v53, v50, v110
	v_mul_f32_e32 v52, v51, v111
	v_mul_f32_e32 v51, v65, v112
	v_mul_f32_e32 v50, v116, v113
	v_bfe_u32 v65, v53, 16, 1
	v_bfe_u32 v111, v51, 16, 1
	v_bfe_u32 v110, v52, 16, 1
	v_bfe_u32 v112, v50, 16, 1
	v_add3_u32 v65, v53, v65, s13
	v_add3_u32 v111, v51, v111, s13
	v_add3_u32 v110, v52, v110, s13
	v_add3_u32 v112, v50, v112, s13
	v_lshrrev_b32_e32 v65, 16, v65
	v_lshrrev_b32_e32 v111, 16, v111
	v_and_or_b32 v110, v110, s14, v65
	v_and_or_b32 v111, v112, s14, v111
	global_store_dwordx2 v[114:115], v[110:111], off offset:1536
	global_load_dwordx4 v[110:113], v[70:71], off
	v_mul_f32_e32 v65, v48, v109
	v_mul_f32_e32 v116, v49, v109
	s_waitcnt vmcnt(0)
	v_mul_f32_e32 v49, v46, v110
	v_mul_f32_e32 v48, v47, v111
	v_mul_f32_e32 v47, v65, v112
	v_mul_f32_e32 v46, v116, v113
	v_bfe_u32 v65, v49, 16, 1
	v_bfe_u32 v111, v47, 16, 1
	v_bfe_u32 v110, v48, 16, 1
	v_bfe_u32 v112, v46, 16, 1
	v_add3_u32 v65, v49, v65, s13
	v_add3_u32 v111, v47, v111, s13
	v_add3_u32 v110, v48, v110, s13
	v_add3_u32 v112, v46, v112, s13
	v_lshrrev_b32_e32 v65, 16, v65
	v_lshrrev_b32_e32 v111, 16, v111
	v_and_or_b32 v110, v110, s14, v65
	v_and_or_b32 v111, v112, s14, v111
	global_store_dwordx2 v[114:115], v[110:111], off offset:2048
	global_load_dwordx4 v[110:113], v[72:73], off
	v_mul_f32_e32 v65, v44, v109
	v_mul_f32_e32 v116, v45, v109
	s_waitcnt vmcnt(0)
	v_mul_f32_e32 v45, v42, v110
	v_mul_f32_e32 v44, v43, v111
	v_mul_f32_e32 v43, v65, v112
	v_mul_f32_e32 v42, v116, v113
	v_bfe_u32 v65, v45, 16, 1
	v_bfe_u32 v111, v43, 16, 1
	v_bfe_u32 v110, v44, 16, 1
	v_bfe_u32 v112, v42, 16, 1
	v_add3_u32 v65, v45, v65, s13
	v_add3_u32 v111, v43, v111, s13
	v_add3_u32 v110, v44, v110, s13
	v_add3_u32 v112, v42, v112, s13
	v_lshrrev_b32_e32 v65, 16, v65
	v_lshrrev_b32_e32 v111, 16, v111
	v_and_or_b32 v110, v110, s14, v65
	v_and_or_b32 v111, v112, s14, v111
	global_store_dwordx2 v[114:115], v[110:111], off offset:2560
	global_load_dwordx4 v[110:113], v[74:75], off
	v_mul_f32_e32 v65, v40, v109
	v_mul_f32_e32 v116, v41, v109
	s_waitcnt vmcnt(0)
	v_mul_f32_e32 v41, v38, v110
	v_mul_f32_e32 v40, v39, v111
	v_mul_f32_e32 v39, v65, v112
	v_mul_f32_e32 v38, v116, v113
	v_bfe_u32 v65, v41, 16, 1
	v_bfe_u32 v111, v39, 16, 1
	v_bfe_u32 v110, v40, 16, 1
	v_bfe_u32 v112, v38, 16, 1
	v_add3_u32 v65, v41, v65, s13
	v_add3_u32 v111, v39, v111, s13
	v_add3_u32 v110, v40, v110, s13
	v_add3_u32 v112, v38, v112, s13
	v_lshrrev_b32_e32 v65, 16, v65
	v_lshrrev_b32_e32 v111, 16, v111
	v_and_or_b32 v110, v110, s14, v65
	v_and_or_b32 v111, v112, s14, v111
	global_store_dwordx2 v[114:115], v[110:111], off offset:3072
	global_load_dwordx4 v[110:113], v[76:77], off
	v_mul_f32_e32 v65, v36, v109
	v_mul_f32_e32 v116, v37, v109
	s_waitcnt vmcnt(0)
	v_mul_f32_e32 v37, v34, v110
	v_mul_f32_e32 v36, v35, v111
	v_mul_f32_e32 v35, v65, v112
	v_mul_f32_e32 v34, v116, v113
	v_bfe_u32 v65, v37, 16, 1
	v_bfe_u32 v111, v35, 16, 1
	v_bfe_u32 v110, v36, 16, 1
	v_bfe_u32 v112, v34, 16, 1
	v_add3_u32 v65, v37, v65, s13
	v_add3_u32 v111, v35, v111, s13
	v_add3_u32 v110, v36, v110, s13
	v_add3_u32 v112, v34, v112, s13
	v_lshrrev_b32_e32 v65, 16, v65
	v_lshrrev_b32_e32 v111, 16, v111
	v_and_or_b32 v110, v110, s14, v65
	v_and_or_b32 v111, v112, s14, v111
	global_store_dwordx2 v[114:115], v[110:111], off offset:3584
	global_load_dwordx4 v[110:113], v[78:79], off
	v_mul_f32_e32 v65, v32, v109
	v_mul_f32_e32 v114, v33, v109
	s_waitcnt vmcnt(0)
	v_mul_f32_e32 v33, v30, v110
	v_mul_f32_e32 v32, v31, v111
	v_mul_f32_e32 v31, v65, v112
	v_mul_f32_e32 v30, v114, v113
	v_bfe_u32 v65, v33, 16, 1
	v_bfe_u32 v111, v31, 16, 1
	v_bfe_u32 v110, v32, 16, 1
	v_bfe_u32 v112, v30, 16, 1
	v_add3_u32 v65, v33, v65, s13
	v_add3_u32 v111, v31, v111, s13
	v_add3_u32 v110, v32, v110, s13
	v_add3_u32 v112, v30, v112, s13
	v_lshrrev_b32_e32 v65, 16, v65
	v_lshrrev_b32_e32 v111, 16, v111
	v_and_or_b32 v110, v110, s14, v65
	v_and_or_b32 v111, v112, s14, v111
	global_store_dwordx2 v[62:63], v[110:111], off
	global_load_dwordx4 v[110:113], v[80:81], off
	v_mul_f32_e32 v65, v28, v109
	v_mul_f32_e32 v114, v29, v109
	s_waitcnt vmcnt(0)
	v_mul_f32_e32 v29, v26, v110
	v_mul_f32_e32 v28, v27, v111
	v_mul_f32_e32 v27, v65, v112
	v_mul_f32_e32 v26, v114, v113
	v_bfe_u32 v65, v29, 16, 1
	v_bfe_u32 v111, v27, 16, 1
	v_bfe_u32 v110, v28, 16, 1
	v_bfe_u32 v112, v26, 16, 1
	v_add3_u32 v65, v29, v65, s13
	v_add3_u32 v111, v27, v111, s13
	v_add3_u32 v110, v28, v110, s13
	v_add3_u32 v112, v26, v112, s13
	v_lshrrev_b32_e32 v65, 16, v65
	v_lshrrev_b32_e32 v111, 16, v111
	v_and_or_b32 v110, v110, s14, v65
	v_and_or_b32 v111, v112, s14, v111
	global_store_dwordx2 v[62:63], v[110:111], off offset:512
	global_load_dwordx4 v[110:113], v[82:83], off
	v_mul_f32_e32 v65, v24, v109
	v_mul_f32_e32 v114, v25, v109
	s_waitcnt vmcnt(0)
	v_mul_f32_e32 v25, v22, v110
	v_mul_f32_e32 v24, v23, v111
	v_mul_f32_e32 v23, v65, v112
	v_mul_f32_e32 v22, v114, v113
	v_bfe_u32 v65, v25, 16, 1
	v_bfe_u32 v111, v23, 16, 1
	v_bfe_u32 v110, v24, 16, 1
	v_bfe_u32 v112, v22, 16, 1
	v_add3_u32 v65, v25, v65, s13
	v_add3_u32 v111, v23, v111, s13
	v_add3_u32 v110, v24, v110, s13
	v_add3_u32 v112, v22, v112, s13
	v_lshrrev_b32_e32 v65, 16, v65
	v_lshrrev_b32_e32 v111, 16, v111
	v_and_or_b32 v110, v110, s14, v65
	v_and_or_b32 v111, v112, s14, v111
	global_store_dwordx2 v[62:63], v[110:111], off offset:1024
	global_load_dwordx4 v[110:113], v[84:85], off
	v_mul_f32_e32 v65, v20, v109
	v_mul_f32_e32 v114, v21, v109
	s_waitcnt vmcnt(0)
	v_mul_f32_e32 v21, v18, v110
	v_mul_f32_e32 v20, v19, v111
	v_mul_f32_e32 v19, v65, v112
	v_mul_f32_e32 v18, v114, v113
	v_bfe_u32 v65, v21, 16, 1
	v_bfe_u32 v111, v19, 16, 1
	v_bfe_u32 v110, v20, 16, 1
	v_bfe_u32 v112, v18, 16, 1
	v_add3_u32 v65, v21, v65, s13
	v_add3_u32 v111, v19, v111, s13
	v_add3_u32 v110, v20, v110, s13
	v_add3_u32 v112, v18, v112, s13
	v_lshrrev_b32_e32 v65, 16, v65
	v_lshrrev_b32_e32 v111, 16, v111
	v_and_or_b32 v110, v110, s14, v65
	v_and_or_b32 v111, v112, s14, v111
	global_store_dwordx2 v[62:63], v[110:111], off offset:1536
	global_load_dwordx4 v[110:113], v[86:87], off
	v_mul_f32_e32 v65, v16, v109
	v_mul_f32_e32 v114, v17, v109
	s_waitcnt vmcnt(0)
	v_mul_f32_e32 v17, v14, v110
	v_mul_f32_e32 v16, v15, v111
	v_mul_f32_e32 v15, v65, v112
	v_mul_f32_e32 v14, v114, v113
	v_bfe_u32 v65, v17, 16, 1
	v_bfe_u32 v111, v15, 16, 1
	v_bfe_u32 v110, v16, 16, 1
	v_bfe_u32 v112, v14, 16, 1
	v_add3_u32 v65, v17, v65, s13
	v_add3_u32 v111, v15, v111, s13
	v_add3_u32 v110, v16, v110, s13
	v_add3_u32 v112, v14, v112, s13
	v_lshrrev_b32_e32 v65, 16, v65
	v_lshrrev_b32_e32 v111, 16, v111
	v_and_or_b32 v110, v110, s14, v65
	v_and_or_b32 v111, v112, s14, v111
	global_store_dwordx2 v[62:63], v[110:111], off offset:2048
	global_load_dwordx4 v[110:113], v[88:89], off
	v_mul_f32_e32 v65, v12, v109
	v_mul_f32_e32 v114, v13, v109
	s_waitcnt vmcnt(0)
	v_mul_f32_e32 v13, v10, v110
	v_mul_f32_e32 v12, v11, v111
	v_mul_f32_e32 v11, v65, v112
	v_mul_f32_e32 v10, v114, v113
	v_bfe_u32 v65, v13, 16, 1
	v_bfe_u32 v111, v11, 16, 1
	v_bfe_u32 v110, v12, 16, 1
	v_bfe_u32 v112, v10, 16, 1
	v_add3_u32 v65, v13, v65, s13
	v_add3_u32 v111, v11, v111, s13
	v_add3_u32 v110, v12, v110, s13
	v_add3_u32 v112, v10, v112, s13
	v_lshrrev_b32_e32 v65, 16, v65
	v_lshrrev_b32_e32 v111, 16, v111
	v_and_or_b32 v110, v110, s14, v65
	v_and_or_b32 v111, v112, s14, v111
	global_store_dwordx2 v[62:63], v[110:111], off offset:2560
	global_load_dwordx4 v[110:113], v[90:91], off
	v_mul_f32_e32 v65, v8, v109
	v_mul_f32_e32 v114, v9, v109
	s_waitcnt vmcnt(0)
	v_mul_f32_e32 v9, v6, v110
	v_mul_f32_e32 v8, v7, v111
	v_mul_f32_e32 v7, v65, v112
	v_mul_f32_e32 v6, v114, v113
	v_bfe_u32 v65, v9, 16, 1
	v_bfe_u32 v111, v7, 16, 1
	v_bfe_u32 v110, v8, 16, 1
	v_bfe_u32 v112, v6, 16, 1
	v_add3_u32 v65, v9, v65, s13
	v_add3_u32 v111, v7, v111, s13
	v_add3_u32 v110, v8, v110, s13
	v_add3_u32 v112, v6, v112, s13
	v_lshrrev_b32_e32 v65, 16, v65
	v_lshrrev_b32_e32 v111, 16, v111
	v_and_or_b32 v110, v110, s14, v65
	v_and_or_b32 v111, v112, s14, v111
	global_store_dwordx2 v[62:63], v[110:111], off offset:3072
	global_load_dwordx4 v[110:113], v[92:93], off
	v_mul_f32_e32 v114, v5, v109
	v_max_f32_e64 v5, |v108|, |v107|
	v_max_f32_e64 v65, |v106|, |v64|
	v_max3_f32 v5, v5, 0, v65
	v_max_f32_e64 v65, |v61|, |v60|
	v_max_f32_e64 v109, |v59|, |v58|
	v_max3_f32 v5, v5, v65, v109
	v_max_f32_e64 v65, |v57|, |v56|
	v_max_f32_e64 v109, |v55|, |v54|
	v_max3_f32 v5, v5, v65, v109
	v_max_f32_e64 v65, |v53|, |v52|
	v_max_f32_e64 v109, |v51|, |v50|
	v_max3_f32 v5, v5, v65, v109
	v_max_f32_e64 v65, |v49|, |v48|
	v_max_f32_e64 v109, |v47|, |v46|
	v_max3_f32 v5, v5, v65, v109
	v_max_f32_e64 v65, |v45|, |v44|
	v_max_f32_e64 v109, |v43|, |v42|
	v_max3_f32 v5, v5, v65, v109
	v_max_f32_e64 v65, |v41|, |v40|
	v_max_f32_e64 v109, |v39|, |v38|
	v_max3_f32 v5, v5, v65, v109
	v_max_f32_e64 v65, |v37|, |v36|
	v_max_f32_e64 v109, |v35|, |v34|
	v_max3_f32 v5, v5, v65, v109
	v_max_f32_e64 v65, |v33|, |v32|
	v_max_f32_e64 v109, |v31|, |v30|
	v_max3_f32 v5, v5, v65, v109
	v_max_f32_e64 v65, |v29|, |v28|
	v_max_f32_e64 v109, |v27|, |v26|
	v_max3_f32 v5, v5, v65, v109
	v_max_f32_e64 v65, |v25|, |v24|
	v_max_f32_e64 v109, |v23|, |v22|
	v_max3_f32 v5, v5, v65, v109
	v_max_f32_e64 v65, |v21|, |v20|
	v_max_f32_e64 v109, |v19|, |v18|
	v_max3_f32 v5, v5, v65, v109
	v_max_f32_e64 v65, |v17|, |v16|
	v_max_f32_e64 v109, |v15|, |v14|
	v_max3_f32 v5, v5, v65, v109
	v_max_f32_e64 v65, |v13|, |v12|
	v_max_f32_e64 v109, |v11|, |v10|
	v_max3_f32 v5, v5, v65, v109
	v_max_f32_e64 v65, |v9|, |v8|
	v_max_f32_e64 v109, |v7|, |v6|
	v_max3_f32 v115, v5, v65, v109
	s_waitcnt vmcnt(0)
	v_mul_f32_e32 v109, v2, v110
	v_mul_f32_e32 v65, v3, v111
	v_mul_f32_e32 v5, v4, v112
	v_mul_f32_e32 v4, v114, v113
	v_max_f32_e64 v2, |v109|, |v65|
	v_max_f32_e64 v3, |v5|, |v4|
	v_max3_f32 v2, v115, v2, v3
	ds_bpermute_b32 v3, v100, v2
	v_bfe_u32 v110, v109, 16, 1
	v_add3_u32 v110, v109, v110, s13
	v_bfe_u32 v111, v65, 16, 1
	v_lshrrev_b32_e32 v110, 16, v110
	s_waitcnt lgkmcnt(0)
	v_max_f32_e32 v3, v3, v3
	v_max_f32_e32 v2, v2, v3
	ds_bpermute_b32 v3, v101, v2
	v_add3_u32 v111, v65, v111, s13
	s_waitcnt lgkmcnt(0)
	v_max_f32_e32 v3, v3, v3
	v_max_f32_e32 v2, v2, v3
	ds_bpermute_b32 v3, v102, v2
	s_waitcnt lgkmcnt(0)
	v_max_f32_e32 v3, v3, v3
	v_max_f32_e32 v2, v2, v3
	ds_bpermute_b32 v3, v103, v2
	s_waitcnt lgkmcnt(0)
	v_max_f32_e32 v3, v3, v3
	v_max_f32_e32 v3, v2, v3
	ds_bpermute_b32 v112, v104, v3
	v_and_or_b32 v2, v111, s14, v110
	v_bfe_u32 v110, v5, 16, 1
	v_add3_u32 v110, v5, v110, s13
	v_lshrrev_b32_e32 v110, 16, v110
	s_waitcnt lgkmcnt(0)
	v_max_f32_e32 v111, v112, v112
	v_max_f32_e32 v111, v3, v111
	ds_bpermute_b32 v112, v105, v111
	v_bfe_u32 v3, v4, 16, 1
	v_add3_u32 v3, v4, v3, s13
	v_and_or_b32 v3, v3, s14, v110
	global_store_dwordx2 v[62:63], v[2:3], off offset:3584
	s_waitcnt lgkmcnt(0)
	v_max3_f32 v2, v111, v112, s23
	s_and_saveexec_b64 s[6:7], s[4:5]
	s_cbranch_execz .LBB0_690
	s_add_u32 s28, s10, s0
	v_mul_f32_e32 v3, 0x3c010204, v2
	s_addc_u32 s29, s11, s1
	global_store_dword v67, v3, s[28:29]
	s_branch .LBB0_690

.LBB0_2768:
	s_or_b64 exec, exec, s[16:17]
	s_waitcnt lgkmcnt(0)
	ds_read_b128 v[36:39], v111
	ds_read_b128 v[48:51], v111 offset:32
	s_lshl_b64 s[18:19], s[74:75], 7
	s_add_u32 s16, s23, s18
	s_addc_u32 s17, s24, s19
	s_waitcnt lgkmcnt(1)
	v_rcp_f32_e32 v47, v36
	v_rcp_f32_e32 v46, v37
	v_rcp_f32_e32 v44, v38
	v_rcp_f32_e32 v42, v39
	v_mul_f32_e32 v20, v20, v47
	v_cvt_pk_bf16_f32 v20, v20, s0
	s_waitcnt lgkmcnt(0)
	v_rcp_f32_e32 v40, v48
	v_rcp_f32_e32 v38, v49
	v_rcp_f32_e32 v37, v50
	v_rcp_f32_e32 v36, v51
	ds_read_b128 v[48:51], v111 offset:64
	ds_read_b128 v[52:55], v111 offset:96
	ds_write_b16 v116, v20
	v_mul_f32_e32 v20, v21, v46
	v_cvt_pk_bf16_f32 v20, v20, s0
	ds_write_b16 v116, v20 offset:80
	v_mul_f32_e32 v20, v22, v44
	v_cvt_pk_bf16_f32 v20, v20, s0
	ds_write_b16 v116, v20 offset:160
	v_mul_f32_e32 v20, v23, v42
	v_cvt_pk_bf16_f32 v20, v20, s0
	ds_write_b16 v116, v20 offset:240
	v_mul_f32_e32 v20, v24, v40
	v_cvt_pk_bf16_f32 v20, v20, s0
	ds_write_b16 v116, v20 offset:640
	v_mul_f32_e32 v20, v25, v38
	v_cvt_pk_bf16_f32 v20, v20, s0
	s_waitcnt lgkmcnt(6)
	v_rcp_f32_e32 v45, v48
	ds_write_b16 v116, v20 offset:720
	v_mul_f32_e32 v20, v26, v37
	v_cvt_pk_bf16_f32 v20, v20, s0
	v_rcp_f32_e32 v43, v49
	ds_write_b16 v116, v20 offset:800
	v_mul_f32_e32 v20, v27, v36
	v_cvt_pk_bf16_f32 v20, v20, s0
	v_rcp_f32_e32 v41, v50
	ds_write_b16 v116, v20 offset:880
	v_mul_f32_e32 v20, v28, v45
	v_cvt_pk_bf16_f32 v20, v20, s0
	v_rcp_f32_e32 v39, v51
	ds_write_b16 v116, v20 offset:1280
	v_mul_f32_e32 v20, v29, v43
	v_cvt_pk_bf16_f32 v20, v20, s0
	s_waitcnt lgkmcnt(9)
	v_rcp_f32_e32 v51, v52
	ds_write_b16 v116, v20 offset:1360
	v_mul_f32_e32 v20, v30, v41
	v_cvt_pk_bf16_f32 v20, v20, s0
	v_rcp_f32_e32 v50, v53
	ds_write_b16 v116, v20 offset:1440
	v_mul_f32_e32 v20, v31, v39
	v_cvt_pk_bf16_f32 v20, v20, s0
	v_rcp_f32_e32 v49, v54
	ds_write_b16 v116, v20 offset:1520
	v_mul_f32_e32 v20, v32, v51
	v_cvt_pk_bf16_f32 v20, v20, s0
	v_rcp_f32_e32 v48, v55
	ds_write_b16 v116, v20 offset:1920
	v_mul_f32_e32 v20, v33, v50
	v_cvt_pk_bf16_f32 v20, v20, s0
	ds_write_b16 v116, v20 offset:2000
	v_mul_f32_e32 v20, v34, v49
	v_cvt_pk_bf16_f32 v20, v20, s0
	ds_write_b16 v116, v20 offset:2080
	v_mul_f32_e32 v20, v35, v48
	v_cvt_pk_bf16_f32 v20, v20, s0
	ds_write_b16 v116, v20 offset:2160
	s_waitcnt lgkmcnt(0)
	v_lshl_add_u64 v[24:25], v[106:107], 0, s[18:19]
	v_lshl_add_u64 v[160:161], v[108:109], 0, s[18:19]
	global_load_dwordx4 v[144:147], v[24:25], off
	global_load_dwordx4 v[148:151], v[160:161], off
	global_load_dwordx4 v[152:155], v[24:25], off offset:64
	global_load_dwordx4 v[156:159], v[160:161], off offset:64
	ds_read_b128 v[20:23], v117
	v_mul_f32_e32 v4, v4, v47
	v_cvt_pk_bf16_f32 v4, v4, s0
	s_add_i32 s25, s25, 1
	s_waitcnt vmcnt(7)
	v_mov_b64_e32 v[86:87], v[70:71]
	s_waitcnt lgkmcnt(0)
	v_lshlrev_b32_e32 v32, 16, v20
	v_and_b32_e32 v33, 0xffff0000, v20
	s_waitcnt vmcnt(6)
	v_mov_b64_e32 v[90:91], v[74:75]
	s_waitcnt vmcnt(5)
	v_mov_b64_e32 v[94:95], v[78:79]
	s_waitcnt vmcnt(4)
	v_mov_b64_e32 v[98:99], v[82:83]
	v_add_u32_e32 v114, 0x500, v114
	s_cmp_lg_u32 s25, 8
	v_mov_b64_e32 v[84:85], v[68:69]
	v_mov_b64_e32 v[88:89], v[72:73]
	v_mov_b64_e32 v[92:93], v[76:77]
	v_mov_b64_e32 v[96:97], v[80:81]
	s_waitcnt vmcnt(3)
	v_lshlrev_b32_e32 v30, 16, v144
	v_mul_f32_e32 v20, 0xbfb8aa3b, v30
	v_exp_f32_e32 v20, v20
	v_and_b32_e32 v31, 0xffff0000, v144
	v_pk_mul_f32 v[32:33], v[32:33], v[30:31]
	v_lshlrev_b32_e32 v26, 16, v145
	v_add_f32_e32 v20, 1.0, v20
	v_rcp_f32_e32 v34, v20
	v_mul_f32_e32 v20, 0xbfb8aa3b, v31
	v_exp_f32_e32 v20, v20
	v_and_b32_e32 v27, 0xffff0000, v145
	v_add_f32_e32 v20, 1.0, v20
	v_rcp_f32_e32 v35, v20
	s_nop 0
	v_pk_mul_f32 v[30:31], v[32:33], v[34:35]
	s_nop 0
	v_cvt_pk_bf16_f32 v20, v30, v31
	v_lshlrev_b32_e32 v30, 16, v21
	v_and_b32_e32 v31, 0xffff0000, v21
	v_mul_f32_e32 v21, 0xbfb8aa3b, v26
	v_exp_f32_e32 v21, v21
	v_pk_mul_f32 v[30:31], v[30:31], v[26:27]
	v_add_f32_e32 v21, 1.0, v21
	v_rcp_f32_e32 v32, v21
	v_mul_f32_e32 v21, 0xbfb8aa3b, v27
	v_exp_f32_e32 v21, v21
	s_nop 0
	v_add_f32_e32 v21, 1.0, v21
	v_rcp_f32_e32 v33, v21
	s_nop 0
	v_pk_mul_f32 v[26:27], v[30:31], v[32:33]
	s_nop 0
	v_cvt_pk_bf16_f32 v21, v26, v27
	v_lshlrev_b32_e32 v26, 16, v146
	v_lshlrev_b32_e32 v30, 16, v22
	v_and_b32_e32 v31, 0xffff0000, v22
	v_mul_f32_e32 v22, 0xbfb8aa3b, v26
	v_exp_f32_e32 v22, v22
	v_and_b32_e32 v27, 0xffff0000, v146
	v_pk_mul_f32 v[30:31], v[30:31], v[26:27]
	v_lshlrev_b32_e32 v28, 16, v23
	v_add_f32_e32 v22, 1.0, v22
	v_rcp_f32_e32 v32, v22
	v_mul_f32_e32 v22, 0xbfb8aa3b, v27
	v_exp_f32_e32 v22, v22
	s_nop 0
	v_add_f32_e32 v22, 1.0, v22
	v_rcp_f32_e32 v33, v22
	s_nop 0
	v_pk_mul_f32 v[26:27], v[30:31], v[32:33]
	s_nop 0
	v_cvt_pk_bf16_f32 v22, v26, v27
	v_lshlrev_b32_e32 v26, 16, v147
	v_and_b32_e32 v27, 0xffff0000, v147
	v_and_b32_e32 v29, 0xffff0000, v23
	v_mul_f32_e32 v23, 0xbfb8aa3b, v26
	v_exp_f32_e32 v23, v23
	v_pk_mul_f32 v[28:29], v[28:29], v[26:27]
	v_add_f32_e32 v23, 1.0, v23
	v_rcp_f32_e32 v30, v23
	v_mul_f32_e32 v23, 0xbfb8aa3b, v27
	v_exp_f32_e32 v23, v23
	s_nop 0
	v_add_f32_e32 v23, 1.0, v23
	v_rcp_f32_e32 v31, v23
	s_nop 0
	v_pk_mul_f32 v[26:27], v[28:29], v[30:31]
	s_nop 0
	v_cvt_pk_bf16_f32 v23, v26, v27
	v_lshl_add_u64 v[26:27], s[16:17], 0, v[100:101]
	v_lshl_add_u64 v[26:27], v[26:27], 0, v[2:3]
	global_store_dwordx4 v[26:27], v[20:23], off
	v_lshl_add_u64 v[28:29], v[108:109], 0, s[18:19]
	ds_read_b128 v[20:23], v117 offset:1280
	s_waitcnt lgkmcnt(0)
	v_lshlrev_b32_e32 v52, 16, v20
	v_and_b32_e32 v53, 0xffff0000, v20
	s_waitcnt vmcnt(3)
	v_lshlrev_b32_e32 v34, 16, v148
	v_mul_f32_e32 v20, 0xbfb8aa3b, v34
	v_exp_f32_e32 v20, v20
	v_and_b32_e32 v35, 0xffff0000, v148
	v_pk_mul_f32 v[52:53], v[52:53], v[34:35]
	v_lshlrev_b32_e32 v30, 16, v149
	v_add_f32_e32 v20, 1.0, v20
	v_rcp_f32_e32 v54, v20
	v_mul_f32_e32 v20, 0xbfb8aa3b, v35
	v_exp_f32_e32 v20, v20
	v_and_b32_e32 v31, 0xffff0000, v149
	v_add_f32_e32 v20, 1.0, v20
	v_rcp_f32_e32 v55, v20
	s_nop 0
	v_pk_mul_f32 v[34:35], v[52:53], v[54:55]
	s_nop 0
	v_cvt_pk_bf16_f32 v20, v34, v35
	v_lshlrev_b32_e32 v34, 16, v21
	v_and_b32_e32 v35, 0xffff0000, v21
	v_mul_f32_e32 v21, 0xbfb8aa3b, v30
	v_exp_f32_e32 v21, v21
	v_pk_mul_f32 v[34:35], v[34:35], v[30:31]
	v_add_f32_e32 v21, 1.0, v21
	v_rcp_f32_e32 v52, v21
	v_mul_f32_e32 v21, 0xbfb8aa3b, v31
	v_exp_f32_e32 v21, v21
	s_nop 0
	v_add_f32_e32 v21, 1.0, v21
	v_rcp_f32_e32 v53, v21
	s_nop 0
	v_pk_mul_f32 v[30:31], v[34:35], v[52:53]
	s_nop 0
	v_cvt_pk_bf16_f32 v21, v30, v31
	v_lshlrev_b32_e32 v30, 16, v150
	v_lshlrev_b32_e32 v34, 16, v22
	v_and_b32_e32 v35, 0xffff0000, v22
	v_mul_f32_e32 v22, 0xbfb8aa3b, v30
	v_exp_f32_e32 v22, v22
	v_and_b32_e32 v31, 0xffff0000, v150
	v_pk_mul_f32 v[34:35], v[34:35], v[30:31]
	v_lshlrev_b32_e32 v32, 16, v23
	v_add_f32_e32 v22, 1.0, v22
	v_rcp_f32_e32 v52, v22
	v_mul_f32_e32 v22, 0xbfb8aa3b, v31
	v_exp_f32_e32 v22, v22
	s_nop 0
	v_add_f32_e32 v22, 1.0, v22
	v_rcp_f32_e32 v53, v22
	s_nop 0
	v_pk_mul_f32 v[30:31], v[34:35], v[52:53]
	s_nop 0
	v_cvt_pk_bf16_f32 v22, v30, v31
	v_lshlrev_b32_e32 v30, 16, v151
	v_and_b32_e32 v31, 0xffff0000, v151
	v_and_b32_e32 v33, 0xffff0000, v23
	v_mul_f32_e32 v23, 0xbfb8aa3b, v30
	v_exp_f32_e32 v23, v23
	v_pk_mul_f32 v[32:33], v[32:33], v[30:31]
	v_add_f32_e32 v23, 1.0, v23
	v_rcp_f32_e32 v34, v23
	v_mul_f32_e32 v23, 0xbfb8aa3b, v31
	v_exp_f32_e32 v23, v23
	s_nop 0
	v_add_f32_e32 v23, 1.0, v23
	v_rcp_f32_e32 v35, v23
	s_nop 0
	v_pk_mul_f32 v[30:31], v[32:33], v[34:35]
	s_nop 0
	v_cvt_pk_bf16_f32 v23, v30, v31
	v_lshl_add_u64 v[30:31], s[16:17], 0, v[102:103]
	v_lshl_add_u64 v[30:31], v[30:31], 0, v[2:3]
	global_store_dwordx4 v[30:31], v[20:23], off
	s_waitcnt lgkmcnt(0)
	ds_write_b16 v116, v4
	v_mul_f32_e32 v4, v5, v46
	v_cvt_pk_bf16_f32 v4, v4, s0
	ds_write_b16 v116, v4 offset:80
	v_mul_f32_e32 v4, v6, v44
	v_cvt_pk_bf16_f32 v4, v4, s0
	ds_write_b16 v116, v4 offset:160
	v_mul_f32_e32 v4, v7, v42
	v_cvt_pk_bf16_f32 v4, v4, s0
	ds_write_b16 v116, v4 offset:240
	v_mul_f32_e32 v4, v8, v40
	v_cvt_pk_bf16_f32 v4, v4, s0
	ds_write_b16 v116, v4 offset:640
	v_mul_f32_e32 v4, v9, v38
	v_cvt_pk_bf16_f32 v4, v4, s0
	ds_write_b16 v116, v4 offset:720
	v_mul_f32_e32 v4, v10, v37
	v_cvt_pk_bf16_f32 v4, v4, s0
	ds_write_b16 v116, v4 offset:800
	v_mul_f32_e32 v4, v11, v36
	v_cvt_pk_bf16_f32 v4, v4, s0
	ds_write_b16 v116, v4 offset:880
	v_mul_f32_e32 v4, v12, v45
	v_cvt_pk_bf16_f32 v4, v4, s0
	ds_write_b16 v116, v4 offset:1280
	v_mul_f32_e32 v4, v13, v43
	v_cvt_pk_bf16_f32 v4, v4, s0
	ds_write_b16 v116, v4 offset:1360
	v_mul_f32_e32 v4, v14, v41
	v_cvt_pk_bf16_f32 v4, v4, s0
	ds_write_b16 v116, v4 offset:1440
	v_mul_f32_e32 v4, v15, v39
	v_cvt_pk_bf16_f32 v4, v4, s0
	ds_write_b16 v116, v4 offset:1520
	v_mul_f32_e32 v4, v16, v51
	v_cvt_pk_bf16_f32 v4, v4, s0
	ds_write_b16 v116, v4 offset:1920
	v_mul_f32_e32 v4, v17, v50
	v_cvt_pk_bf16_f32 v4, v4, s0
	ds_write_b16 v116, v4 offset:2000
	v_mul_f32_e32 v4, v18, v49
	v_cvt_pk_bf16_f32 v4, v4, s0
	ds_write_b16 v116, v4 offset:2080
	v_mul_f32_e32 v4, v19, v48
	v_cvt_pk_bf16_f32 v4, v4, s0
	ds_write_b16 v116, v4 offset:2160
	s_waitcnt lgkmcnt(0)
	ds_read_b128 v[4:7], v117
	s_waitcnt lgkmcnt(0)
	v_lshlrev_b32_e32 v14, 16, v4
	v_and_b32_e32 v15, 0xffff0000, v4
	s_waitcnt vmcnt(3)
	v_lshlrev_b32_e32 v12, 16, v152
	v_mul_f32_e32 v4, 0xbfb8aa3b, v12
	v_exp_f32_e32 v4, v4
	v_and_b32_e32 v13, 0xffff0000, v152
	v_pk_mul_f32 v[14:15], v[14:15], v[12:13]
	v_lshlrev_b32_e32 v8, 16, v153
	v_add_f32_e32 v4, 1.0, v4
	v_rcp_f32_e32 v16, v4
	v_mul_f32_e32 v4, 0xbfb8aa3b, v13
	v_exp_f32_e32 v4, v4
	v_and_b32_e32 v9, 0xffff0000, v153
	v_add_f32_e32 v4, 1.0, v4
	v_rcp_f32_e32 v17, v4
	s_nop 0
	v_pk_mul_f32 v[12:13], v[14:15], v[16:17]
	s_nop 0
	v_cvt_pk_bf16_f32 v4, v12, v13
	v_lshlrev_b32_e32 v12, 16, v5
	v_and_b32_e32 v13, 0xffff0000, v5
	v_mul_f32_e32 v5, 0xbfb8aa3b, v8
	v_exp_f32_e32 v5, v5
	v_pk_mul_f32 v[12:13], v[12:13], v[8:9]
	v_add_f32_e32 v5, 1.0, v5
	v_rcp_f32_e32 v14, v5
	v_mul_f32_e32 v5, 0xbfb8aa3b, v9
	v_exp_f32_e32 v5, v5
	s_nop 0
	v_add_f32_e32 v5, 1.0, v5
	v_rcp_f32_e32 v15, v5
	s_nop 0
	v_pk_mul_f32 v[8:9], v[12:13], v[14:15]
	s_nop 0
	v_cvt_pk_bf16_f32 v5, v8, v9
	v_lshlrev_b32_e32 v8, 16, v154
	v_lshlrev_b32_e32 v12, 16, v6
	v_and_b32_e32 v13, 0xffff0000, v6
	v_mul_f32_e32 v6, 0xbfb8aa3b, v8
	v_exp_f32_e32 v6, v6
	v_and_b32_e32 v9, 0xffff0000, v154
	v_pk_mul_f32 v[12:13], v[12:13], v[8:9]
	v_lshlrev_b32_e32 v10, 16, v7
	v_add_f32_e32 v6, 1.0, v6
	v_rcp_f32_e32 v14, v6
	v_mul_f32_e32 v6, 0xbfb8aa3b, v9
	v_exp_f32_e32 v6, v6
	s_nop 0
	v_add_f32_e32 v6, 1.0, v6
	v_rcp_f32_e32 v15, v6
	s_nop 0
	v_pk_mul_f32 v[8:9], v[12:13], v[14:15]
	s_nop 0
	v_cvt_pk_bf16_f32 v6, v8, v9
	v_lshlrev_b32_e32 v8, 16, v155
	v_and_b32_e32 v9, 0xffff0000, v155
	v_and_b32_e32 v11, 0xffff0000, v7
	v_mul_f32_e32 v7, 0xbfb8aa3b, v8
	v_exp_f32_e32 v7, v7
	v_pk_mul_f32 v[10:11], v[10:11], v[8:9]
	v_add_f32_e32 v7, 1.0, v7
	v_rcp_f32_e32 v12, v7
	v_mul_f32_e32 v7, 0xbfb8aa3b, v9
	v_exp_f32_e32 v7, v7
	s_nop 0
	v_add_f32_e32 v7, 1.0, v7
	v_rcp_f32_e32 v13, v7
	s_nop 0
	v_pk_mul_f32 v[8:9], v[10:11], v[12:13]
	s_nop 0
	v_cvt_pk_bf16_f32 v7, v8, v9
	global_store_dwordx4 v[26:27], v[4:7], off offset:64
	ds_read_b128 v[4:7], v117 offset:1280
	s_waitcnt lgkmcnt(0)
	v_lshlrev_b32_e32 v14, 16, v4
	v_and_b32_e32 v15, 0xffff0000, v4
	s_waitcnt vmcnt(3)
	v_lshlrev_b32_e32 v12, 16, v156
	v_mul_f32_e32 v4, 0xbfb8aa3b, v12
	v_exp_f32_e32 v4, v4
	v_and_b32_e32 v13, 0xffff0000, v156
	v_pk_mul_f32 v[14:15], v[14:15], v[12:13]
	v_lshlrev_b32_e32 v8, 16, v157
	v_add_f32_e32 v4, 1.0, v4
	v_rcp_f32_e32 v16, v4
	v_mul_f32_e32 v4, 0xbfb8aa3b, v13
	v_exp_f32_e32 v4, v4
	v_and_b32_e32 v9, 0xffff0000, v157
	v_add_f32_e32 v4, 1.0, v4
	v_rcp_f32_e32 v17, v4
	s_nop 0
	v_pk_mul_f32 v[12:13], v[14:15], v[16:17]
	s_nop 0
	v_cvt_pk_bf16_f32 v4, v12, v13
	v_lshlrev_b32_e32 v12, 16, v5
	v_and_b32_e32 v13, 0xffff0000, v5
	v_mul_f32_e32 v5, 0xbfb8aa3b, v8
	v_exp_f32_e32 v5, v5
	v_pk_mul_f32 v[12:13], v[12:13], v[8:9]
	v_add_f32_e32 v5, 1.0, v5
	v_rcp_f32_e32 v14, v5
	v_mul_f32_e32 v5, 0xbfb8aa3b, v9
	v_exp_f32_e32 v5, v5
	s_nop 0
	v_add_f32_e32 v5, 1.0, v5
	v_rcp_f32_e32 v15, v5
	s_nop 0
	v_pk_mul_f32 v[8:9], v[12:13], v[14:15]
	s_nop 0
	v_cvt_pk_bf16_f32 v5, v8, v9
	v_lshlrev_b32_e32 v8, 16, v158
	v_lshlrev_b32_e32 v12, 16, v6
	v_and_b32_e32 v13, 0xffff0000, v6
	v_mul_f32_e32 v6, 0xbfb8aa3b, v8
	v_exp_f32_e32 v6, v6
	v_and_b32_e32 v9, 0xffff0000, v158
	v_pk_mul_f32 v[12:13], v[12:13], v[8:9]
	v_lshlrev_b32_e32 v10, 16, v7
	v_add_f32_e32 v6, 1.0, v6
	v_rcp_f32_e32 v14, v6
	v_mul_f32_e32 v6, 0xbfb8aa3b, v9
	v_exp_f32_e32 v6, v6
	s_nop 0
	v_add_f32_e32 v6, 1.0, v6
	v_rcp_f32_e32 v15, v6
	s_nop 0
	v_pk_mul_f32 v[8:9], v[12:13], v[14:15]
	s_nop 0
	v_cvt_pk_bf16_f32 v6, v8, v9
	v_lshlrev_b32_e32 v8, 16, v159
	v_and_b32_e32 v9, 0xffff0000, v159
	v_and_b32_e32 v11, 0xffff0000, v7
	v_mul_f32_e32 v7, 0xbfb8aa3b, v8
	v_exp_f32_e32 v7, v7
	v_pk_mul_f32 v[10:11], v[10:11], v[8:9]
	v_add_f32_e32 v7, 1.0, v7
	v_rcp_f32_e32 v12, v7
	v_mul_f32_e32 v7, 0xbfb8aa3b, v9
	v_exp_f32_e32 v7, v7
	s_nop 0
	v_add_f32_e32 v7, 1.0, v7
	v_rcp_f32_e32 v13, v7
	s_nop 0
	v_pk_mul_f32 v[8:9], v[10:11], v[12:13]
	s_nop 0
	v_cvt_pk_bf16_f32 v7, v8, v9
	global_store_dwordx4 v[30:31], v[4:7], off offset:64
	s_waitcnt lgkmcnt(0)
	s_waitcnt lgkmcnt(0)
	s_cbranch_scc0 .LBB0_2739
